# residual epilogue: row sum-of-squares reduction uses DPP adds for the xor-8/4/2/1 steps (one LDS round trip instead of five) on top of the exact vmcnt waits
# speedup vs baseline: 1.0030x; 1.0028x over previous
; DI unsigned pk2(float a, float b) { f32x2 v = {a, b}; bf16x2_t r = __builtin_convertvector(v, bf16x2_t); return __builtin_bit_cast(unsigned, r); }
; template <int NJ> DI void resid_epilogue(float* __restrict__ x, bf16_t* __restrict__ xb, float* __restrict__ ssn, int mt, int nt, const float* cl, float scale) {
;     ...
; #pragma unroll 4
;   for (int it = 0; it < NP; ++it) {
;     const int row = r0 + RPP * it;
;     const f32x4 c = *(const f32x4*)(cl + row * CLD + c4);
;     const size_t gi = (size_t)(mt * 128 + row) * DM + nt * (64 * NJ) + c4;
;     f32x4 xv = *(const f32x4*)(x + gi);
;     xv = xv + scale * c;
;     *(f32x4*)(x + gi) = xv;
;     u32x2 p; p.x = pk2(xv[0], xv[1]); p.y = pk2(xv[2], xv[3]);
;     *(u32x2*)(xb + (size_t)(mt * 128 + row) * LDX + nt * (64 * NJ) + c4) = p;
;     float s_ = xv[0] * xv[0] + xv[1] * xv[1] + xv[2] * xv[2] + xv[3] * xv[3];
;     if (NJ == 2) s_ += __shfl_xor(s_, 16);
;     s_ += __shfl_xor(s_, 8); s_ += __shfl_xor(s_, 4); s_ += __shfl_xor(s_, 2); s_ += __shfl_xor(s_, 1);
;     if ((tid & (LPR - 1)) == 0) atomicAdd(ssn + mt * 128 + row, s_);
;   }
.LBB0_429:
	v_lshl_add_u64 v[20:21], v[6:7], 0, s[0:1]
	s_waitcnt lgkmcnt(0)
	global_load_dwordx4 v[28:31], v[20:21], off
	v_lshl_add_u64 v[38:39], v[16:17], 0, s[0:1]
	global_load_dwordx4 v[44:47], v[38:39], off
	v_lshl_add_u64 v[40:41], v[10:11], 0, s[0:1]
	global_load_dwordx4 v[48:51], v[40:41], off
	v_lshl_add_u64 v[42:43], v[4:5], 0, s[0:1]
	global_load_dwordx4 v[52:55], v[42:43], off
	ds_read_b128 v[32:35], v27
	s_waitcnt vmcnt(3) lgkmcnt(0)
	v_pk_fma_f32 v[28:29], v[32:33], 0.5, v[28:29] op_sel_hi:[1,0,1]
	s_nop 0
	v_mul_f32_e32 v0, v29, v29
	v_pk_fma_f32 v[30:31], v[34:35], 0.5, v[30:31] op_sel_hi:[1,0,1]
	v_fmac_f32_e32 v0, v28, v28
	v_fmac_f32_e32 v0, v30, v30
	v_fmac_f32_e32 v0, v31, v31
	ds_bpermute_b32 v32, v22, v0
	global_store_dwordx4 v[20:21], v[28:31], off
	v_cvt_pk_bf16_f32 v20, v28, v29
	v_cvt_pk_bf16_f32 v21, v30, v31
	v_lshl_add_u64 v[30:31], s[94:95], 0, v[18:19]
	s_waitcnt lgkmcnt(0)
	v_add_f32_e32 v0, v0, v32
	s_nop 1
	v_add_f32_dpp v0, v0, v0 quad_perm:[1,0,3,2] row_mask:0xf bank_mask:0xf
	s_nop 1
	v_add_f32_dpp v0, v0, v0 quad_perm:[2,3,0,1] row_mask:0xf bank_mask:0xf
	s_nop 1
	v_add_f32_dpp v0, v0, v0 row_half_mirror row_mask:0xf bank_mask:0xf
	s_nop 1
	v_add_f32_dpp v0, v0, v0 row_mirror row_mask:0xf bank_mask:0xf
	global_store_dwordx2 v[30:31], v[20:21], off
	v_lshl_add_u64 v[20:21], s[94:95], 0, v[12:13]
	s_and_saveexec_b64 s[2:3], vcc
	s_cbranch_execz .LBB0_431
	global_atomic_add_f32 v[20:21], v0, off offset:-64
.LBB0_431:
	s_or_b64 exec, exec, s[2:3]
	v_lshl_add_u64 v[36:37], v[16:17], 0, s[0:1]
	s_waitcnt lgkmcnt(0)
	ds_read_b128 v[32:35], v27 offset:4224
	s_waitcnt vmcnt(5) lgkmcnt(0)
	v_pk_fma_f32 v[32:33], v[32:33], 0.5, v[44:45] op_sel_hi:[1,0,1]
	s_nop 0
	v_mul_f32_e32 v0, v33, v33
	v_pk_fma_f32 v[34:35], v[34:35], 0.5, v[46:47] op_sel_hi:[1,0,1]
	v_fmac_f32_e32 v0, v32, v32
	v_fmac_f32_e32 v0, v34, v34
	v_fmac_f32_e32 v0, v35, v35
	ds_bpermute_b32 v28, v22, v0
	global_store_dwordx4 v[36:37], v[32:35], off
	v_cvt_pk_bf16_f32 v30, v32, v33
	v_cvt_pk_bf16_f32 v31, v34, v35
	v_lshl_add_u64 v[32:33], s[94:95], 0, v[14:15]
	s_waitcnt lgkmcnt(0)
	v_add_f32_e32 v0, v0, v28
	s_nop 1
	v_add_f32_dpp v0, v0, v0 quad_perm:[1,0,3,2] row_mask:0xf bank_mask:0xf
	s_nop 1
	v_add_f32_dpp v0, v0, v0 quad_perm:[2,3,0,1] row_mask:0xf bank_mask:0xf
	s_nop 1
	v_add_f32_dpp v0, v0, v0 row_half_mirror row_mask:0xf bank_mask:0xf
	s_nop 1
	v_add_f32_dpp v0, v0, v0 row_mirror row_mask:0xf bank_mask:0xf
	global_store_dwordx2 v[32:33], v[30:31], off
	s_and_saveexec_b64 s[2:3], vcc
	s_cbranch_execz .LBB0_433
	global_atomic_add_f32 v[20:21], v0, off offset:-32
.LBB0_433:
	s_or_b64 exec, exec, s[2:3]
	v_lshl_add_u64 v[36:37], v[10:11], 0, s[0:1]
	s_waitcnt lgkmcnt(0)
	ds_read_b128 v[32:35], v27 offset:8448
	s_waitcnt vmcnt(7) lgkmcnt(0)
	v_pk_fma_f32 v[32:33], v[32:33], 0.5, v[48:49] op_sel_hi:[1,0,1]
	s_nop 0
	v_mul_f32_e32 v0, v33, v33
	v_pk_fma_f32 v[34:35], v[34:35], 0.5, v[50:51] op_sel_hi:[1,0,1]
	v_fmac_f32_e32 v0, v32, v32
	v_fmac_f32_e32 v0, v34, v34
	v_fmac_f32_e32 v0, v35, v35
	ds_bpermute_b32 v28, v22, v0
	global_store_dwordx4 v[36:37], v[32:35], off
	v_cvt_pk_bf16_f32 v30, v32, v33
	v_cvt_pk_bf16_f32 v31, v34, v35
	v_lshl_add_u64 v[32:33], s[94:95], 0, v[8:9]
	s_waitcnt lgkmcnt(0)
	v_add_f32_e32 v0, v0, v28
	s_nop 1
	v_add_f32_dpp v0, v0, v0 quad_perm:[1,0,3,2] row_mask:0xf bank_mask:0xf
	s_nop 1
	v_add_f32_dpp v0, v0, v0 quad_perm:[2,3,0,1] row_mask:0xf bank_mask:0xf
	s_nop 1
	v_add_f32_dpp v0, v0, v0 row_half_mirror row_mask:0xf bank_mask:0xf
	s_nop 1
	v_add_f32_dpp v0, v0, v0 row_mirror row_mask:0xf bank_mask:0xf
	global_store_dwordx2 v[32:33], v[30:31], off
	s_and_saveexec_b64 s[2:3], vcc
	s_cbranch_execz .LBB0_435
	global_atomic_add_f32 v[20:21], v0, off
.LBB0_435:
	s_or_b64 exec, exec, s[2:3]
	v_lshl_add_u64 v[36:37], v[4:5], 0, s[0:1]
	s_waitcnt lgkmcnt(0)
	ds_read_b128 v[32:35], v27 offset:12672
	s_waitcnt vmcnt(9) lgkmcnt(0)
	v_pk_fma_f32 v[32:33], v[32:33], 0.5, v[52:53] op_sel_hi:[1,0,1]
	s_nop 0
	v_mul_f32_e32 v0, v33, v33
	v_pk_fma_f32 v[34:35], v[34:35], 0.5, v[54:55] op_sel_hi:[1,0,1]
	v_fmac_f32_e32 v0, v32, v32
	v_fmac_f32_e32 v0, v34, v34
	v_fmac_f32_e32 v0, v35, v35
	ds_bpermute_b32 v28, v22, v0
	global_store_dwordx4 v[36:37], v[32:35], off
	v_cvt_pk_bf16_f32 v30, v32, v33
	v_cvt_pk_bf16_f32 v31, v34, v35
	v_lshl_add_u64 v[32:33], s[94:95], 0, v[2:3]
	s_waitcnt lgkmcnt(0)
	v_add_f32_e32 v0, v0, v28
	s_nop 1
	v_add_f32_dpp v0, v0, v0 quad_perm:[1,0,3,2] row_mask:0xf bank_mask:0xf
	s_nop 1
	v_add_f32_dpp v0, v0, v0 quad_perm:[2,3,0,1] row_mask:0xf bank_mask:0xf
	s_nop 1
	v_add_f32_dpp v0, v0, v0 row_half_mirror row_mask:0xf bank_mask:0xf
	s_nop 1
	v_add_f32_dpp v0, v0, v0 row_mirror row_mask:0xf bank_mask:0xf
	global_store_dwordx2 v[32:33], v[30:31], off
	s_and_saveexec_b64 s[2:3], vcc
	s_cbranch_execz .LBB0_428
	global_atomic_add_f32 v[20:21], v0, off offset:32
	s_branch .LBB0_428

; DI unsigned pk2(float a, float b) { f32x2 v = {a, b}; bf16x2_t r = __builtin_convertvector(v, bf16x2_t); return __builtin_bit_cast(unsigned, r); }
; template <int NJ> DI void resid_epilogue(float* __restrict__ x, bf16_t* __restrict__ xb, float* __restrict__ ssn, int mt, int nt, const float* cl, float scale) {
;     ...
; #pragma unroll 4
;   for (int it = 0; it < NP; ++it) {
;     const int row = r0 + RPP * it;
;     const f32x4 c = *(const f32x4*)(cl + row * CLD + c4);
;     const size_t gi = (size_t)(mt * 128 + row) * DM + nt * (64 * NJ) + c4;
;     f32x4 xv = *(const f32x4*)(x + gi);
;     xv = xv + scale * c;
;     *(f32x4*)(x + gi) = xv;
;     u32x2 p; p.x = pk2(xv[0], xv[1]); p.y = pk2(xv[2], xv[3]);
;     *(u32x2*)(xb + (size_t)(mt * 128 + row) * LDX + nt * (64 * NJ) + c4) = p;
;     float s_ = xv[0] * xv[0] + xv[1] * xv[1] + xv[2] * xv[2] + xv[3] * xv[3];
;     if (NJ == 2) s_ += __shfl_xor(s_, 16);
;     s_ += __shfl_xor(s_, 8); s_ += __shfl_xor(s_, 4); s_ += __shfl_xor(s_, 2); s_ += __shfl_xor(s_, 1);
;     if ((tid & (LPR - 1)) == 0) atomicAdd(ssn + mt * 128 + row, s_);
;   }
.LBB0_1027:
	v_lshl_add_u64 v[20:21], v[6:7], 0, s[0:1]
	s_waitcnt lgkmcnt(0)
	global_load_dwordx4 v[28:31], v[20:21], off
	v_lshl_add_u64 v[38:39], v[16:17], 0, s[0:1]
	global_load_dwordx4 v[44:47], v[38:39], off
	v_lshl_add_u64 v[40:41], v[10:11], 0, s[0:1]
	global_load_dwordx4 v[48:51], v[40:41], off
	v_lshl_add_u64 v[42:43], v[4:5], 0, s[0:1]
	global_load_dwordx4 v[52:55], v[42:43], off
	ds_read_b128 v[32:35], v27
	s_waitcnt vmcnt(3) lgkmcnt(0)
	v_pk_add_f32 v[28:29], v[32:33], v[28:29]
	s_nop 0
	v_mul_f32_e32 v0, v29, v29
	v_pk_add_f32 v[30:31], v[34:35], v[30:31]
	v_fmac_f32_e32 v0, v28, v28
	v_fmac_f32_e32 v0, v30, v30
	v_fmac_f32_e32 v0, v31, v31
	ds_bpermute_b32 v32, v22, v0
	global_store_dwordx4 v[20:21], v[28:31], off
	v_cvt_pk_bf16_f32 v20, v28, v29
	v_cvt_pk_bf16_f32 v21, v30, v31
	v_lshl_add_u64 v[30:31], s[94:95], 0, v[18:19]
	s_waitcnt lgkmcnt(0)
	v_add_f32_e32 v0, v0, v32
	s_nop 1
	v_add_f32_dpp v0, v0, v0 quad_perm:[1,0,3,2] row_mask:0xf bank_mask:0xf
	s_nop 1
	v_add_f32_dpp v0, v0, v0 quad_perm:[2,3,0,1] row_mask:0xf bank_mask:0xf
	s_nop 1
	v_add_f32_dpp v0, v0, v0 row_half_mirror row_mask:0xf bank_mask:0xf
	s_nop 1
	v_add_f32_dpp v0, v0, v0 row_mirror row_mask:0xf bank_mask:0xf
	global_store_dwordx2 v[30:31], v[20:21], off
	v_lshl_add_u64 v[20:21], s[94:95], 0, v[12:13]
	s_and_saveexec_b64 s[2:3], vcc
	s_cbranch_execz .LBB0_1029
	global_atomic_add_f32 v[20:21], v0, off offset:-64
.LBB0_1029:
	s_or_b64 exec, exec, s[2:3]
	v_lshl_add_u64 v[36:37], v[16:17], 0, s[0:1]
	s_waitcnt lgkmcnt(0)
	ds_read_b128 v[32:35], v27 offset:4224
	s_waitcnt vmcnt(5) lgkmcnt(0)
	v_pk_add_f32 v[32:33], v[32:33], v[44:45]
	s_nop 0
	v_mul_f32_e32 v0, v33, v33
	v_pk_add_f32 v[34:35], v[34:35], v[46:47]
	v_fmac_f32_e32 v0, v32, v32
	v_fmac_f32_e32 v0, v34, v34
	v_fmac_f32_e32 v0, v35, v35
	ds_bpermute_b32 v28, v22, v0
	global_store_dwordx4 v[36:37], v[32:35], off
	v_cvt_pk_bf16_f32 v30, v32, v33
	v_cvt_pk_bf16_f32 v31, v34, v35
	v_lshl_add_u64 v[32:33], s[94:95], 0, v[14:15]
	s_waitcnt lgkmcnt(0)
	v_add_f32_e32 v0, v0, v28
	s_nop 1
	v_add_f32_dpp v0, v0, v0 quad_perm:[1,0,3,2] row_mask:0xf bank_mask:0xf
	s_nop 1
	v_add_f32_dpp v0, v0, v0 quad_perm:[2,3,0,1] row_mask:0xf bank_mask:0xf
	s_nop 1
	v_add_f32_dpp v0, v0, v0 row_half_mirror row_mask:0xf bank_mask:0xf
	s_nop 1
	v_add_f32_dpp v0, v0, v0 row_mirror row_mask:0xf bank_mask:0xf
	global_store_dwordx2 v[32:33], v[30:31], off
	s_and_saveexec_b64 s[2:3], vcc
	s_cbranch_execz .LBB0_1031
	global_atomic_add_f32 v[20:21], v0, off offset:-32
.LBB0_1031:
	s_or_b64 exec, exec, s[2:3]
	v_lshl_add_u64 v[36:37], v[10:11], 0, s[0:1]
	s_waitcnt lgkmcnt(0)
	ds_read_b128 v[32:35], v27 offset:8448
	s_waitcnt vmcnt(7) lgkmcnt(0)
	v_pk_add_f32 v[32:33], v[32:33], v[48:49]
	s_nop 0
	v_mul_f32_e32 v0, v33, v33
	v_pk_add_f32 v[34:35], v[34:35], v[50:51]
	v_fmac_f32_e32 v0, v32, v32
	v_fmac_f32_e32 v0, v34, v34
	v_fmac_f32_e32 v0, v35, v35
	ds_bpermute_b32 v28, v22, v0
	global_store_dwordx4 v[36:37], v[32:35], off
	v_cvt_pk_bf16_f32 v30, v32, v33
	v_cvt_pk_bf16_f32 v31, v34, v35
	v_lshl_add_u64 v[32:33], s[94:95], 0, v[8:9]
	s_waitcnt lgkmcnt(0)
	v_add_f32_e32 v0, v0, v28
	s_nop 1
	v_add_f32_dpp v0, v0, v0 quad_perm:[1,0,3,2] row_mask:0xf bank_mask:0xf
	s_nop 1
	v_add_f32_dpp v0, v0, v0 quad_perm:[2,3,0,1] row_mask:0xf bank_mask:0xf
	s_nop 1
	v_add_f32_dpp v0, v0, v0 row_half_mirror row_mask:0xf bank_mask:0xf
	s_nop 1
	v_add_f32_dpp v0, v0, v0 row_mirror row_mask:0xf bank_mask:0xf
	global_store_dwordx2 v[32:33], v[30:31], off
	s_and_saveexec_b64 s[2:3], vcc
	s_cbranch_execz .LBB0_1033
	global_atomic_add_f32 v[20:21], v0, off
.LBB0_1033:
	s_or_b64 exec, exec, s[2:3]
	v_lshl_add_u64 v[36:37], v[4:5], 0, s[0:1]
	s_waitcnt lgkmcnt(0)
	ds_read_b128 v[32:35], v27 offset:12672
	s_waitcnt vmcnt(9) lgkmcnt(0)
	v_pk_add_f32 v[32:33], v[32:33], v[52:53]
	s_nop 0
	v_mul_f32_e32 v0, v33, v33
	v_pk_add_f32 v[34:35], v[34:35], v[54:55]
	v_fmac_f32_e32 v0, v32, v32
	v_fmac_f32_e32 v0, v34, v34
	v_fmac_f32_e32 v0, v35, v35
	ds_bpermute_b32 v28, v22, v0
	global_store_dwordx4 v[36:37], v[32:35], off
	v_cvt_pk_bf16_f32 v30, v32, v33
	v_cvt_pk_bf16_f32 v31, v34, v35
	v_lshl_add_u64 v[32:33], s[94:95], 0, v[2:3]
	s_waitcnt lgkmcnt(0)
	v_add_f32_e32 v0, v0, v28
	s_nop 1
	v_add_f32_dpp v0, v0, v0 quad_perm:[1,0,3,2] row_mask:0xf bank_mask:0xf
	s_nop 1
	v_add_f32_dpp v0, v0, v0 quad_perm:[2,3,0,1] row_mask:0xf bank_mask:0xf
	s_nop 1
	v_add_f32_dpp v0, v0, v0 row_half_mirror row_mask:0xf bank_mask:0xf
	s_nop 1
	v_add_f32_dpp v0, v0, v0 row_mirror row_mask:0xf bank_mask:0xf
	global_store_dwordx2 v[32:33], v[30:31], off
	s_and_saveexec_b64 s[2:3], vcc
	s_cbranch_execz .LBB0_1026
	global_atomic_add_f32 v[20:21], v0, off offset:32
	s_branch .LBB0_1026

; DI unsigned pk2(float a, float b) { f32x2 v = {a, b}; bf16x2_t r = __builtin_convertvector(v, bf16x2_t); return __builtin_bit_cast(unsigned, r); }
; template <int NJ> DI void resid_epilogue(float* __restrict__ x, bf16_t* __restrict__ xb, float* __restrict__ ssn, int mt, int nt, const float* cl, float scale) {
;     ...
; #pragma unroll 4
;   for (int it = 0; it < NP; ++it) {
;     const int row = r0 + RPP * it;
;     const f32x4 c = *(const f32x4*)(cl + row * CLD + c4);
;     const size_t gi = (size_t)(mt * 128 + row) * DM + nt * (64 * NJ) + c4;
;     f32x4 xv = *(const f32x4*)(x + gi);
;     xv = xv + scale * c;
;     *(f32x4*)(x + gi) = xv;
;     u32x2 p; p.x = pk2(xv[0], xv[1]); p.y = pk2(xv[2], xv[3]);
;     *(u32x2*)(xb + (size_t)(mt * 128 + row) * LDX + nt * (64 * NJ) + c4) = p;
;     float s_ = xv[0] * xv[0] + xv[1] * xv[1] + xv[2] * xv[2] + xv[3] * xv[3];
;     if (NJ == 2) s_ += __shfl_xor(s_, 16);
;     s_ += __shfl_xor(s_, 8); s_ += __shfl_xor(s_, 4); s_ += __shfl_xor(s_, 2); s_ += __shfl_xor(s_, 1);
;     if ((tid & (LPR - 1)) == 0) atomicAdd(ssn + mt * 128 + row, s_);
;   }
.LBB0_1228:
	v_lshl_add_u64 v[20:21], v[6:7], 0, s[0:1]
	s_waitcnt lgkmcnt(0)
	global_load_dwordx4 v[28:31], v[20:21], off
	v_lshl_add_u64 v[38:39], v[16:17], 0, s[0:1]
	global_load_dwordx4 v[44:47], v[38:39], off
	v_lshl_add_u64 v[40:41], v[10:11], 0, s[0:1]
	global_load_dwordx4 v[48:51], v[40:41], off
	v_lshl_add_u64 v[42:43], v[4:5], 0, s[0:1]
	global_load_dwordx4 v[52:55], v[42:43], off
	ds_read_b128 v[32:35], v27
	s_waitcnt vmcnt(3) lgkmcnt(0)
	v_pk_add_f32 v[28:29], v[32:33], v[28:29]
	s_nop 0
	v_mul_f32_e32 v0, v29, v29
	v_pk_add_f32 v[30:31], v[34:35], v[30:31]
	v_fmac_f32_e32 v0, v28, v28
	v_fmac_f32_e32 v0, v30, v30
	v_fmac_f32_e32 v0, v31, v31
	ds_bpermute_b32 v32, v22, v0
	global_store_dwordx4 v[20:21], v[28:31], off
	v_cvt_pk_bf16_f32 v20, v28, v29
	v_cvt_pk_bf16_f32 v21, v30, v31
	v_lshl_add_u64 v[30:31], s[94:95], 0, v[18:19]
	s_waitcnt lgkmcnt(0)
	v_add_f32_e32 v0, v0, v32
	s_nop 1
	v_add_f32_dpp v0, v0, v0 quad_perm:[1,0,3,2] row_mask:0xf bank_mask:0xf
	s_nop 1
	v_add_f32_dpp v0, v0, v0 quad_perm:[2,3,0,1] row_mask:0xf bank_mask:0xf
	s_nop 1
	v_add_f32_dpp v0, v0, v0 row_half_mirror row_mask:0xf bank_mask:0xf
	s_nop 1
	v_add_f32_dpp v0, v0, v0 row_mirror row_mask:0xf bank_mask:0xf
	global_store_dwordx2 v[30:31], v[20:21], off
	v_lshl_add_u64 v[20:21], s[94:95], 0, v[12:13]
	s_and_saveexec_b64 s[2:3], s[36:37]
	s_cbranch_execz .LBB0_1230
	global_atomic_add_f32 v[20:21], v0, off offset:-64
.LBB0_1230:
	s_or_b64 exec, exec, s[2:3]
	v_lshl_add_u64 v[36:37], v[16:17], 0, s[0:1]
	s_waitcnt lgkmcnt(0)
	ds_read_b128 v[32:35], v27 offset:4224
	s_waitcnt vmcnt(5) lgkmcnt(0)
	v_pk_add_f32 v[32:33], v[32:33], v[44:45]
	s_nop 0
	v_mul_f32_e32 v0, v33, v33
	v_pk_add_f32 v[34:35], v[34:35], v[46:47]
	v_fmac_f32_e32 v0, v32, v32
	v_fmac_f32_e32 v0, v34, v34
	v_fmac_f32_e32 v0, v35, v35
	ds_bpermute_b32 v28, v22, v0
	global_store_dwordx4 v[36:37], v[32:35], off
	v_cvt_pk_bf16_f32 v30, v32, v33
	v_cvt_pk_bf16_f32 v31, v34, v35
	v_lshl_add_u64 v[32:33], s[94:95], 0, v[14:15]
	s_waitcnt lgkmcnt(0)
	v_add_f32_e32 v0, v0, v28
	s_nop 1
	v_add_f32_dpp v0, v0, v0 quad_perm:[1,0,3,2] row_mask:0xf bank_mask:0xf
	s_nop 1
	v_add_f32_dpp v0, v0, v0 quad_perm:[2,3,0,1] row_mask:0xf bank_mask:0xf
	s_nop 1
	v_add_f32_dpp v0, v0, v0 row_half_mirror row_mask:0xf bank_mask:0xf
	s_nop 1
	v_add_f32_dpp v0, v0, v0 row_mirror row_mask:0xf bank_mask:0xf
	global_store_dwordx2 v[32:33], v[30:31], off
	s_and_saveexec_b64 s[2:3], s[36:37]
	s_cbranch_execz .LBB0_1232
	global_atomic_add_f32 v[20:21], v0, off offset:-32
.LBB0_1232:
	s_or_b64 exec, exec, s[2:3]
	v_lshl_add_u64 v[36:37], v[10:11], 0, s[0:1]
	s_waitcnt lgkmcnt(0)
	ds_read_b128 v[32:35], v27 offset:8448
	s_waitcnt vmcnt(7) lgkmcnt(0)
	v_pk_add_f32 v[32:33], v[32:33], v[48:49]
	s_nop 0
	v_mul_f32_e32 v0, v33, v33
	v_pk_add_f32 v[34:35], v[34:35], v[50:51]
	v_fmac_f32_e32 v0, v32, v32
	v_fmac_f32_e32 v0, v34, v34
	v_fmac_f32_e32 v0, v35, v35
	ds_bpermute_b32 v28, v22, v0
	global_store_dwordx4 v[36:37], v[32:35], off
	v_cvt_pk_bf16_f32 v30, v32, v33
	v_cvt_pk_bf16_f32 v31, v34, v35
	v_lshl_add_u64 v[32:33], s[94:95], 0, v[8:9]
	s_waitcnt lgkmcnt(0)
	v_add_f32_e32 v0, v0, v28
	s_nop 1
	v_add_f32_dpp v0, v0, v0 quad_perm:[1,0,3,2] row_mask:0xf bank_mask:0xf
	s_nop 1
	v_add_f32_dpp v0, v0, v0 quad_perm:[2,3,0,1] row_mask:0xf bank_mask:0xf
	s_nop 1
	v_add_f32_dpp v0, v0, v0 row_half_mirror row_mask:0xf bank_mask:0xf
	s_nop 1
	v_add_f32_dpp v0, v0, v0 row_mirror row_mask:0xf bank_mask:0xf
	global_store_dwordx2 v[32:33], v[30:31], off
	s_and_saveexec_b64 s[2:3], s[36:37]
	s_cbranch_execz .LBB0_1234
	global_atomic_add_f32 v[20:21], v0, off
.LBB0_1234:
	s_or_b64 exec, exec, s[2:3]
	v_lshl_add_u64 v[36:37], v[4:5], 0, s[0:1]
	s_waitcnt lgkmcnt(0)
	ds_read_b128 v[32:35], v27 offset:12672
	s_waitcnt vmcnt(9) lgkmcnt(0)
	v_pk_add_f32 v[32:33], v[32:33], v[52:53]
	s_nop 0
	v_mul_f32_e32 v0, v33, v33
	v_pk_add_f32 v[34:35], v[34:35], v[54:55]
	v_fmac_f32_e32 v0, v32, v32
	v_fmac_f32_e32 v0, v34, v34
	v_fmac_f32_e32 v0, v35, v35
	ds_bpermute_b32 v28, v22, v0
	global_store_dwordx4 v[36:37], v[32:35], off
	v_cvt_pk_bf16_f32 v30, v32, v33
	v_cvt_pk_bf16_f32 v31, v34, v35
	v_lshl_add_u64 v[32:33], s[94:95], 0, v[2:3]
	s_waitcnt lgkmcnt(0)
	v_add_f32_e32 v0, v0, v28
	s_nop 1
	v_add_f32_dpp v0, v0, v0 quad_perm:[1,0,3,2] row_mask:0xf bank_mask:0xf
	s_nop 1
	v_add_f32_dpp v0, v0, v0 quad_perm:[2,3,0,1] row_mask:0xf bank_mask:0xf
	s_nop 1
	v_add_f32_dpp v0, v0, v0 row_half_mirror row_mask:0xf bank_mask:0xf
	s_nop 1
	v_add_f32_dpp v0, v0, v0 row_mirror row_mask:0xf bank_mask:0xf
	global_store_dwordx2 v[32:33], v[30:31], off
	s_and_saveexec_b64 s[2:3], s[36:37]
	s_cbranch_execz .LBB0_1227
	global_atomic_add_f32 v[20:21], v0, off offset:32
	s_branch .LBB0_1227
